# layer-1 out-proj weight transposition moved from the layer-0 MLP-up tail to the layer-1 in-proj tail (the MLP-up tail was the fullest)
# baseline (speedup 1.0000x reference)
.Ltr_a_m4_end:
	s_cmp_eq_u32 s81, 0
	s_cbranch_scc1 .Ltr_a_m5_end
	s_load_dwordx2 s[64:65], s[76:77], 0x98
	s_waitcnt lgkmcnt(0)
	s_add_u32 s64, s64, 0x1000000
	s_addc_u32 s65, s65, 0
	s_mov_b32 s69, 0x6800000
	s_add_u32 s66, s82, s69
	s_addc_u32 s67, s83, 0
	s_mov_b32 s68, 0x4000
	s_mov_b32 s61, 2048
	s_mov_b32 s60, s63
	v_mov_b32_e32 v2, 0x800
	v_mul_u32_u24_e32 v2, v2, v55
	v_add_lshl_u32 v2, v2, v54, 2
	v_mov_b32_e32 v52, 0x1000
	v_mul_u32_u24_e32 v52, v52, v54
	v_lshl_add_u32 v52, v55, 6, v52

.Ltr_b_m3_loop:
	s_cmp_ge_u32 s60, s61
	s_cbranch_scc1 .Ltr_b_m3_end
	s_and_b32 s71, s60, 63
	s_lshr_b32 s70, s60, 6
	s_mul_i32 s69, s70, 0x80000
	s_lshl_b32 s80, s71, 7
	s_add_u32 s69, s69, s80
	s_add_u32 s72, s64, s69
	s_addc_u32 s73, s65, 0
	s_mul_i32 s69, s71, 0x8000
	s_lshl_b32 s80, s70, 7
	s_add_u32 s69, s69, s80
	s_add_u32 s74, s66, s69
	s_addc_u32 s75, s67, 0
	v_mov_b32_e32 v3, v2
	global_load_dword v4, v3, s[72:73] nt
	v_add_u32_e32 v3, s68, v3
	global_load_dword v5, v3, s[72:73] nt
	v_add_u32_e32 v3, s68, v3
	global_load_dword v6, v3, s[72:73] nt
	v_add_u32_e32 v3, s68, v3
	global_load_dword v7, v3, s[72:73] nt
	v_add_u32_e32 v3, s68, v3
	global_load_dword v8, v3, s[72:73] nt
	v_add_u32_e32 v3, s68, v3
	global_load_dword v9, v3, s[72:73] nt
	v_add_u32_e32 v3, s68, v3
	global_load_dword v10, v3, s[72:73] nt
	v_add_u32_e32 v3, s68, v3
	global_load_dword v11, v3, s[72:73] nt
	v_add_u32_e32 v3, s68, v3
	global_load_dword v12, v3, s[72:73] nt
	v_add_u32_e32 v3, s68, v3
	global_load_dword v13, v3, s[72:73] nt
	v_add_u32_e32 v3, s68, v3
	global_load_dword v14, v3, s[72:73] nt
	v_add_u32_e32 v3, s68, v3
	global_load_dword v15, v3, s[72:73] nt
	v_add_u32_e32 v3, s68, v3
	global_load_dword v16, v3, s[72:73] nt
	v_add_u32_e32 v3, s68, v3
	global_load_dword v17, v3, s[72:73] nt
	v_add_u32_e32 v3, s68, v3
	global_load_dword v18, v3, s[72:73] nt
	v_add_u32_e32 v3, s68, v3
	global_load_dword v19, v3, s[72:73] nt
	v_add_u32_e32 v3, s68, v3
	global_load_dword v20, v3, s[72:73] nt
	v_add_u32_e32 v3, s68, v3
	global_load_dword v21, v3, s[72:73] nt
	v_add_u32_e32 v3, s68, v3
	global_load_dword v22, v3, s[72:73] nt
	v_add_u32_e32 v3, s68, v3
	global_load_dword v23, v3, s[72:73] nt
	v_add_u32_e32 v3, s68, v3
	global_load_dword v24, v3, s[72:73] nt
	v_add_u32_e32 v3, s68, v3
	global_load_dword v25, v3, s[72:73] nt
	v_add_u32_e32 v3, s68, v3
	global_load_dword v26, v3, s[72:73] nt
	v_add_u32_e32 v3, s68, v3
	global_load_dword v27, v3, s[72:73] nt
	v_add_u32_e32 v3, s68, v3
	global_load_dword v28, v3, s[72:73] nt
	v_add_u32_e32 v3, s68, v3
	global_load_dword v29, v3, s[72:73] nt
	v_add_u32_e32 v3, s68, v3
	global_load_dword v30, v3, s[72:73] nt
	v_add_u32_e32 v3, s68, v3
	global_load_dword v31, v3, s[72:73] nt
	v_add_u32_e32 v3, s68, v3
	global_load_dword v32, v3, s[72:73] nt
	v_add_u32_e32 v3, s68, v3
	global_load_dword v33, v3, s[72:73] nt
	v_add_u32_e32 v3, s68, v3
	global_load_dword v34, v3, s[72:73] nt
	v_add_u32_e32 v3, s68, v3
	global_load_dword v35, v3, s[72:73] nt
	s_waitcnt vmcnt(0)
	v_permlane32_swap_b32_e32 v4, v20
	v_permlane32_swap_b32_e32 v5, v21
	v_permlane32_swap_b32_e32 v6, v22
	v_permlane32_swap_b32_e32 v7, v23
	v_permlane32_swap_b32_e32 v8, v24
	v_permlane32_swap_b32_e32 v9, v25
	v_permlane32_swap_b32_e32 v10, v26
	v_permlane32_swap_b32_e32 v11, v27
	v_permlane32_swap_b32_e32 v12, v28
	v_permlane32_swap_b32_e32 v13, v29
	v_permlane32_swap_b32_e32 v14, v30
	v_permlane32_swap_b32_e32 v15, v31
	v_permlane32_swap_b32_e32 v16, v32
	v_permlane32_swap_b32_e32 v17, v33
	v_permlane32_swap_b32_e32 v18, v34
	v_permlane32_swap_b32_e32 v19, v35
	v_cvt_pk_bf16_f32 v36, v4, v20
	v_cvt_pk_bf16_f32 v37, v5, v21
	v_cvt_pk_bf16_f32 v38, v6, v22
	v_cvt_pk_bf16_f32 v39, v7, v23
	v_cvt_pk_bf16_f32 v40, v8, v24
	v_cvt_pk_bf16_f32 v41, v9, v25
	v_cvt_pk_bf16_f32 v42, v10, v26
	v_cvt_pk_bf16_f32 v43, v11, v27
	v_cvt_pk_bf16_f32 v44, v12, v28
	v_cvt_pk_bf16_f32 v45, v13, v29
	v_cvt_pk_bf16_f32 v46, v14, v30
	v_cvt_pk_bf16_f32 v47, v15, v31
	v_cvt_pk_bf16_f32 v48, v16, v32
	v_cvt_pk_bf16_f32 v49, v17, v33
	v_cvt_pk_bf16_f32 v50, v18, v34
	v_cvt_pk_bf16_f32 v51, v19, v35
	global_store_dwordx4 v52, v[36:39], s[74:75]
	global_store_dwordx4 v52, v[40:43], s[74:75] offset:16
	global_store_dwordx4 v52, v[44:47], s[74:75] offset:32
	global_store_dwordx4 v52, v[48:51], s[74:75] offset:48
	s_add_u32 s60, s60, s62
	s_branch .Ltr_b_m3_loop
.Ltr_b_m3_end:
	v_readlane_b32 vcc_hi, v1, 24
	v_readlane_b32 s60, v1, 0
	v_readlane_b32 s61, v1, 1
	v_readlane_b32 s62, v1, 2
	v_readlane_b32 s63, v1, 3
	v_readlane_b32 s64, v1, 4
	v_readlane_b32 s65, v1, 5
	v_readlane_b32 s66, v1, 6
	v_readlane_b32 s67, v1, 7
	v_readlane_b32 s68, v1, 8
	v_readlane_b32 s69, v1, 9
	v_readlane_b32 s70, v1, 10
	v_readlane_b32 s71, v1, 11
	v_readlane_b32 s72, v1, 12
	v_readlane_b32 s73, v1, 13
	v_readlane_b32 s74, v1, 14
	v_readlane_b32 s75, v1, 15
	v_readlane_b32 s76, v1, 16
	v_readlane_b32 s77, v1, 17
	v_readlane_b32 s78, v1, 18
	v_readlane_b32 s79, v1, 19
	v_readlane_b32 s80, v1, 20
	v_readlane_b32 s81, v1, 21
	v_readlane_b32 s82, v1, 22
	v_readlane_b32 s83, v1, 23
	ds_read_b128 v[4:7], v0
	ds_read_b128 v[8:11], v0 offset:1024
	ds_read_b128 v[12:15], v0 offset:2048
	ds_read_b128 v[16:19], v0 offset:3072
	ds_read_b128 v[20:23], v0 offset:4096
	ds_read_b128 v[24:27], v0 offset:5120
	ds_read_b128 v[28:31], v0 offset:6144
	ds_read_b128 v[32:35], v0 offset:7168
	ds_read_b128 v[36:39], v0 offset:8192
	ds_read_b128 v[40:43], v0 offset:9216
	ds_read_b128 v[44:47], v0 offset:10240
	ds_read_b128 v[48:51], v0 offset:11264
	ds_read_b128 v[52:55], v0 offset:12288
	s_lshl_b32 vcc_lo, s3, 10
	s_mov_b32 m0, vcc_lo
	s_nop 0
	ds_read_addtid_b32 v0 offset:0
	ds_read_addtid_b32 v1 offset:256
	ds_read_addtid_b32 v2 offset:512
	ds_read_addtid_b32 v3 offset:768
	s_waitcnt lgkmcnt(0)
	s_mov_b32 m0, vcc_hi
